# norm phases: adaLN shift/scale rows staged once per phase in LDS instead of L2 loads per row pair
# speedup vs baseline: 1.0014x; 1.0014x over previous
.LBB0_146:
	v_mov_b32_e32 v0, v188
	v_mov_b32_e32 v2, 0x21d28
	v_mov_b32_e32 v4, 0x21c40
	v_add_u32_e32 v2, 0, v2
	ds_read_b64 v[2:3], v2
	v_mov_b32_e32 v6, 0x21d28
	v_add_u32_e32 v4, 0, v4
	ds_read_b64 v[4:5], v4
	v_ashrrev_i32_e32 v1, 6, v0
	v_add_u32_e32 v6, 0, v6
	ds_read_b64 v[6:7], v6
	v_readlane_b32 s0, v238, 7
	s_waitcnt lgkmcnt(2)
	v_readfirstlane_b32 s2, v3
	v_readfirstlane_b32 s4, v2
	v_add_u32_e32 v24, s0, v1
	s_mov_b32 s0, 0xa000
	s_waitcnt lgkmcnt(1)
	v_readfirstlane_b32 s5, v5
	v_readfirstlane_b32 s6, v4
	s_waitcnt lgkmcnt(0)
	v_readfirstlane_b32 s7, v7
	v_readfirstlane_b32 s8, v6
	v_cmp_gt_i32_e32 vcc, s0, v24
	s_mul_i32 s69, s52, 9
	s_and_saveexec_b64 s[0:1], vcc
	s_cbranch_execz .LBB0_169
	s_add_u32 s10, s8, 0x6078000
	s_addc_u32 s11, s7, 0
	s_lshl_b32 s7, s52, 13
	s_add_u32 s6, s6, s7
	s_addc_u32 s7, s5, 0
	v_lshlrev_b32_e32 v1, 2, v0
	s_add_u32 s4, s4, 0x2bc0000
	v_and_b32_e32 v26, 0xfc, v1
	v_ashrrev_i32_e32 v25, 31, v24
	s_addc_u32 s5, s2, 0
	v_lshlrev_b32_e32 v164, 2, v26
	v_lshlrev_b64 v[2:3], 11, v[24:25]
	v_and_b32_e32 v0, 63, v0
	s_cmp_lg_u32 s52, 0
	s_movk_i32 s2, 0x80
	v_lshl_add_u64 v[28:29], s[6:7], 0, v[164:165]
	v_lshlrev_b32_e32 v164, 1, v26
	v_lshl_or_b32 v2, v0, 3, v2
	s_cselect_b64 s[8:9], -1, 0
	v_bitop3_b32 v27, v1, s2, v193 bitop3:0x6c
	v_or_b32_e32 v30, 0x100, v26
	v_or_b32_e32 v32, 0x200, v26
	v_or_b32_e32 v34, 0x300, v26
	v_lshl_add_u64 v[36:37], s[10:11], 0, v[164:165]
	v_lshl_add_u64 v[38:39], s[10:11], 0, v[2:3]
	s_mov_b64 s[10:11], 0
	s_mov_b64 s[12:13], 0
	v_mov_b32_e32 v40, v24
	global_load_dwordx4 v[198:201], v[28:29], off
	global_load_dwordx4 v[202:205], v[28:29], off offset:1024
	global_load_dwordx4 v[206:209], v[28:29], off offset:2048
	global_load_dwordx4 v[210:213], v[28:29], off offset:3072
	s_mul_i32 s100, s69, 0x6000
	s_add_u32 s100, s4, s100
	s_addc_u32 s101, s5, 0
	v_lshlrev_b32_e32 v234, 4, v188
	global_load_dwordx4 v[214:217], v234, s[100:101]
	s_add_u32 s100, s100, 0x6000
	s_addc_u32 s101, s101, 0
	global_load_dwordx4 v[218:221], v234, s[100:101]
	s_add_u32 s100, s100, 0x6000
	s_addc_u32 s101, s101, 0
	global_load_dwordx4 v[222:225], v234, s[100:101]
	s_add_u32 s100, s100, 0x6000
	s_addc_u32 s101, s101, 0
	global_load_dwordx4 v[226:229], v234, s[100:101]
	s_add_u32 s100, s100, 0x6000
	s_addc_u32 s101, s101, 0
	global_load_dwordx4 v[230:233], v234, s[100:101]
	s_add_u32 s100, s100, 0x6000
	s_addc_u32 s101, s101, 0
	global_load_dwordx4 v[240:243], v234, s[100:101]
	s_add_u32 s100, s100, 0x6000
	s_addc_u32 s101, s101, 0
	global_load_dwordx4 v[244:247], v234, s[100:101]
	s_add_u32 s100, s100, 0x6000
	s_addc_u32 s101, s101, 0
	global_load_dwordx4 v[248:251], v234, s[100:101]
	s_add_u32 s100, s100, 0x6000
	s_addc_u32 s101, s101, 0
	global_load_dwordx4 v[252:255], v234, s[100:101]
	s_add_u32 s100, s100, 0x6000
	s_addc_u32 s101, s101, 0
	s_sub_u32 s101, s100, 0x35000
	v_add_u32_e32 v235, 0xa000, v234
	v_add_u32_e32 v234, 0xc000, v234
	s_waitcnt vmcnt(0)
	ds_write_b128 v235, v[214:217]
	ds_write_b128 v235, v[218:221] offset:8192
	ds_write_b128 v235, v[222:225] offset:16384
	ds_write_b128 v235, v[226:229] offset:24576
	ds_write_b128 v235, v[230:233] offset:32768
	ds_write_b128 v235, v[240:243] offset:40960
	ds_write_b128 v235, v[244:247] offset:49152
	ds_write_b128 v235, v[248:251] offset:57344
	ds_write_b128 v234, v[252:255] offset:57344
	s_waitcnt lgkmcnt(0)
	s_barrier
	s_branch .LBB0_149

.LBB0_167:
	s_or_b64 exec, exec, s[14:15]
	v_add_u32_e32 v31, 0xffffe000, v40
	v_lshrrev_b32_e32 v31, 12, v31
	v_add_u32_e32 v31, 1, v31
	v_cmp_lt_i32_e32 vcc, s48, v40
	v_mov_b64_e32 v[70:71], s[4:5]
	s_waitcnt vmcnt(3)
	v_mov_b32_e32 v86, v21
	v_cndmask_b32_e32 v31, 0, v31, vcc
	v_add_u32_e32 v31, s69, v31
	v_mad_u64_u32 v[74:75], s[6:7], v31, s50, v[70:71]
	v_lshl_add_u64 v[82:83], v[74:75], 0, s[58:59]
	v_lshl_add_u64 v[84:85], v[74:75], 0, v[164:165]
	v_lshl_add_u64 v[78:79], v[82:83], 0, v[164:165]
	s_nop 0
	v_mov_b32_e32 v252, v78
	v_mov_b32_e32 v253, v79
	v_subrev_u32_e32 v234, s101, v252
	v_lshrrev_b32_e32 v235, 13, v234
	v_mul_u32_u24_e32 v235, 0xab, v235
	v_lshrrev_b32_e32 v235, 9, v235
	v_and_b32_e32 v234, 0x1fff, v234
	v_lshl_add_u32 v234, v235, 13, v234
	v_add_u32_e32 v234, 0xa000, v234
	ds_read_b128 v[214:217], v234
	ds_read_b128 v[218:221], v234 offset:1024
	ds_read_b128 v[222:225], v234 offset:2048
	ds_read_b128 v[226:229], v234 offset:3072
	ds_read_b128 v[230:233], v234 offset:4096
	ds_read_b128 v[240:243], v234 offset:5120
	ds_read_b128 v[244:247], v234 offset:6144
	ds_read_b128 v[248:251], v234 offset:7168
	s_waitcnt vmcnt(0) lgkmcnt(0)
	v_mov_b32_e32 v70, v198
	v_mov_b32_e32 v71, v199
	v_mov_b32_e32 v72, v200
	v_mov_b32_e32 v73, v201
	v_mov_b32_e32 v74, v214
	v_mov_b32_e32 v75, v215
	v_mov_b32_e32 v76, v216
	v_mov_b32_e32 v77, v217
	v_mov_b32_e32 v78, v230
	v_mov_b32_e32 v79, v231
	v_mov_b32_e32 v80, v232
	v_mov_b32_e32 v81, v233
	v_mov_b32_e32 v87, v17
	v_mov_b32_e32 v68, v20
	v_mov_b32_e32 v69, v16
	v_pk_mul_f32 v[86:87], v[86:87], v[86:87]
	v_mov_b32_e32 v88, v22
	v_mov_b32_e32 v89, v18
	v_pk_fma_f32 v[68:69], v[68:69], v[68:69], v[86:87]
	v_mov_b32_e32 v90, v23
	v_pk_fma_f32 v[68:69], v[88:89], v[88:89], v[68:69]
	v_mov_b32_e32 v88, v13
	v_mov_b32_e32 v89, v9
	v_mov_b32_e32 v91, v19
	v_mov_b32_e32 v86, v12
	v_mov_b32_e32 v87, v8
	v_pk_mul_f32 v[88:89], v[88:89], v[88:89]
	v_pk_fma_f32 v[68:69], v[90:91], v[90:91], v[68:69]
	v_mov_b32_e32 v90, v14
	v_mov_b32_e32 v91, v10
	v_pk_fma_f32 v[86:87], v[86:87], v[86:87], v[88:89]
	v_mov_b32_e32 v92, v15
	v_mov_b32_e32 v93, v11
	v_pk_fma_f32 v[86:87], v[90:91], v[90:91], v[86:87]
	v_add_f32_e32 v31, v68, v69
	v_pk_fma_f32 v[86:87], v[92:93], v[92:93], v[86:87]
	v_lshlrev_b32_e32 v68, 2, v30
	v_add_f32_e32 v31, v31, v86
	v_add_f32_e32 v31, v31, v87
	ds_bpermute_b32 v33, v27, v31
	v_mov_b32_e32 v69, v165
	v_lshl_add_u64 v[86:87], v[82:83], 0, v[68:69]
	s_waitcnt lgkmcnt(0)
	v_add_f32_e32 v31, v31, v33
	ds_swizzle_b32 v33, v31 offset:swizzle(SWAP,16)
	s_waitcnt lgkmcnt(0)
	v_add_f32_e32 v31, v31, v33
	ds_swizzle_b32 v33, v31 offset:swizzle(SWAP,8)
	s_waitcnt lgkmcnt(0)
	v_add_f32_e32 v31, v31, v33
	ds_swizzle_b32 v33, v31 offset:swizzle(SWAP,4)
	s_waitcnt lgkmcnt(0)
	v_add_f32_e32 v31, v31, v33
	ds_swizzle_b32 v33, v31 offset:swizzle(SWAP,2)
	s_waitcnt lgkmcnt(0)
	v_add_f32_e32 v31, v31, v33
	ds_swizzle_b32 v33, v31 offset:swizzle(SWAP,1)
	s_waitcnt lgkmcnt(0)
	v_add_f32_e32 v31, v31, v33
	v_fmamk_f32 v31, v31, 0x3a800000, v189
	v_mul_f32_e32 v33, 0x4b800000, v31
	v_cmp_gt_f32_e32 vcc, s28, v31
	v_add_f32_e32 v35, 1.0, v79
	s_nop 0
	v_cndmask_b32_e32 v31, v31, v33, vcc
	v_rsq_f32_e32 v31, v31
	v_add_f32_e32 v41, 1.0, v80
	v_add_f32_e32 v51, 1.0, v81
	v_mul_f32_e32 v33, 0x45800000, v31
	v_cndmask_b32_e32 v31, v31, v33, vcc
	v_mul_f32_e32 v20, v20, v31
	v_mul_f32_e32 v21, v21, v31
	v_mul_f32_e32 v22, v22, v31
	v_mul_f32_e32 v23, v23, v31
	v_mul_f32_e32 v20, v70, v20
	v_mul_f32_e32 v21, v71, v21
	v_add_f32_e32 v33, 1.0, v78
	v_mul_f32_e32 v22, v72, v22
	v_mul_f32_e32 v23, v73, v23
	v_fma_f32 v20, v33, v20, v74
	v_fma_f32 v21, v35, v21, v75
	v_fma_f32 v22, v22, v41, v76
	v_fmac_f32_e32 v77, v23, v51
	v_cvt_pk_bf16_f32 v20, v20, v21
	v_cvt_pk_bf16_f32 v21, v22, v77
	global_store_dwordx2 v[38:39], v[20:21], off
	v_mov_b32_e32 v70, v202
	v_mov_b32_e32 v71, v203
	v_mov_b32_e32 v72, v204
	v_mov_b32_e32 v73, v205
	v_mov_b32_e32 v74, v240
	v_mov_b32_e32 v75, v241
	v_mov_b32_e32 v76, v242
	v_mov_b32_e32 v77, v243
	v_mov_b32_e32 v78, v218
	v_mov_b32_e32 v79, v219
	v_mov_b32_e32 v80, v220
	v_mov_b32_e32 v81, v221
	v_mul_f32_e32 v16, v16, v31
	v_mul_f32_e32 v17, v17, v31
	v_mul_f32_e32 v18, v18, v31
	v_mul_f32_e32 v19, v19, v31
	v_lshlrev_b32_e32 v20, 2, v32
	v_mov_b32_e32 v21, v165
	v_lshl_add_u64 v[22:23], v[82:83], 0, v[20:21]
	v_mul_f32_e32 v12, v12, v31
	v_mul_f32_e32 v13, v13, v31
	v_mul_f32_e32 v14, v14, v31
	v_mul_f32_e32 v15, v15, v31
	v_mul_f32_e32 v8, v8, v31
	v_mul_f32_e32 v9, v9, v31
	v_mul_f32_e32 v10, v10, v31
	v_mul_f32_e32 v11, v11, v31
	v_mul_f32_e32 v16, v16, v70
	v_add_f32_e32 v33, 1.0, v74
	v_mul_f32_e32 v17, v17, v71
	v_add_f32_e32 v35, 1.0, v75
	v_mul_f32_e32 v18, v18, v72
	v_add_f32_e32 v41, 1.0, v76
	v_mul_f32_e32 v19, v19, v73
	v_add_f32_e32 v51, 1.0, v77
	v_fma_f32 v16, v16, v33, v78
	v_fma_f32 v17, v17, v35, v79
	v_fma_f32 v18, v18, v41, v80
	v_fmac_f32_e32 v81, v19, v51
	v_cvt_pk_bf16_f32 v16, v16, v17
	v_cvt_pk_bf16_f32 v17, v18, v81
	global_store_dwordx2 v[38:39], v[16:17], off offset:512
	v_mov_b32_e32 v70, v206
	v_mov_b32_e32 v71, v207
	v_mov_b32_e32 v72, v208
	v_mov_b32_e32 v73, v209
	v_mov_b32_e32 v74, v244
	v_mov_b32_e32 v75, v245
	v_mov_b32_e32 v76, v246
	v_mov_b32_e32 v77, v247
	v_mov_b32_e32 v78, v222
	v_mov_b32_e32 v79, v223
	v_mov_b32_e32 v80, v224
	v_mov_b32_e32 v81, v225
	v_lshlrev_b32_e32 v16, 2, v34
	v_mov_b32_e32 v17, v165
	v_lshl_add_u64 v[18:19], v[82:83], 0, v[16:17]
	v_mul_f32_e32 v12, v12, v70
	v_add_f32_e32 v22, 1.0, v74
	v_mul_f32_e32 v13, v13, v71
	v_add_f32_e32 v23, 1.0, v75
	v_mul_f32_e32 v14, v14, v72
	v_add_f32_e32 v33, 1.0, v76
	v_mul_f32_e32 v15, v15, v73
	v_add_f32_e32 v35, 1.0, v77
	v_fma_f32 v12, v12, v22, v78
	v_fma_f32 v13, v13, v23, v79
	v_fma_f32 v14, v14, v33, v80
	v_fmac_f32_e32 v81, v15, v35
	v_cvt_pk_bf16_f32 v12, v12, v13
	v_cvt_pk_bf16_f32 v13, v14, v81
	global_store_dwordx2 v[38:39], v[12:13], off offset:1024
	v_mov_b32_e32 v12, v210
	v_mov_b32_e32 v13, v211
	v_mov_b32_e32 v14, v212
	v_mov_b32_e32 v15, v213
	s_nop 0
	v_mov_b32_e32 v70, v248
	v_mov_b32_e32 v71, v249
	v_mov_b32_e32 v72, v250
	v_mov_b32_e32 v73, v251
	v_mov_b32_e32 v74, v226
	v_mov_b32_e32 v75, v227
	v_mov_b32_e32 v76, v228
	v_mov_b32_e32 v77, v229
	v_mul_f32_e32 v8, v8, v12
	v_add_f32_e32 v12, 1.0, v70
	v_mul_f32_e32 v9, v9, v13
	v_add_f32_e32 v13, 1.0, v71
	v_mul_f32_e32 v10, v10, v14
	v_add_f32_e32 v14, 1.0, v72
	v_mul_f32_e32 v11, v11, v15
	v_add_f32_e32 v15, 1.0, v73
	v_fma_f32 v8, v8, v12, v74
	v_fma_f32 v9, v9, v13, v75
	v_fma_f32 v10, v10, v14, v76
	v_fmac_f32_e32 v77, v11, v15
	v_cvt_pk_bf16_f32 v8, v8, v9
	v_cvt_pk_bf16_f32 v9, v10, v77
	global_store_dwordx2 v[38:39], v[8:9], off offset:1536
	s_and_saveexec_b64 s[14:15], s[34:35]
	s_cbranch_execz .LBB0_148
	v_add_u32_e32 v8, 0xffffe000, v50
	v_lshrrev_b32_e32 v8, 12, v8
	v_add_u32_e32 v8, 1, v8
	v_cmp_lt_i32_e32 vcc, s48, v50
	v_mov_b64_e32 v[12:13], s[4:5]
	v_pk_mul_f32 v[60:61], v[60:61], v[60:61]
	v_cndmask_b32_e32 v8, 0, v8, vcc
	v_add_u32_e32 v14, s69, v8
	v_mad_u64_u32 v[18:19], s[6:7], v14, s50, v[12:13]
	v_lshl_add_u64 v[22:23], v[18:19], 0, s[58:59]
	v_lshl_add_u64 v[12:13], v[22:23], 0, v[164:165]
	v_lshl_add_u64 v[74:75], v[18:19], 0, v[164:165]
	v_pk_mul_f32 v[18:19], v[66:67], v[66:67]
	v_mov_b32_e32 v254, v12
	v_mov_b32_e32 v255, v13
	v_cmp_ne_u64_e32 vcc, v[254:255], v[252:253]
	s_nop 1
	s_and_b64 vcc, exec, vcc
	s_cbranch_vccz .Lnorm_same_cond_1
	v_subrev_u32_e32 v234, s101, v254
	v_lshrrev_b32_e32 v235, 13, v234
	v_mul_u32_u24_e32 v235, 0xab, v235
	v_lshrrev_b32_e32 v235, 9, v235
	v_and_b32_e32 v234, 0x1fff, v234
	v_lshl_add_u32 v234, v235, 13, v234
	v_add_u32_e32 v234, 0xa000, v234
	ds_read_b128 v[214:217], v234
	ds_read_b128 v[218:221], v234 offset:1024
	ds_read_b128 v[222:225], v234 offset:2048
	ds_read_b128 v[226:229], v234 offset:3072
	ds_read_b128 v[230:233], v234 offset:4096
	ds_read_b128 v[240:243], v234 offset:5120
	ds_read_b128 v[244:247], v234 offset:6144
	ds_read_b128 v[248:251], v234 offset:7168
.Lnorm_same_cond_1:
	s_waitcnt vmcnt(0) lgkmcnt(0)
	v_mov_b32_e32 v8, v198
	v_mov_b32_e32 v9, v199
	v_mov_b32_e32 v10, v200
	v_mov_b32_e32 v11, v201
	v_mov_b32_e32 v12, v230
	v_mov_b32_e32 v13, v231
	v_mov_b32_e32 v14, v232
	v_mov_b32_e32 v15, v233
	v_mov_b32_e32 v70, v214
	v_mov_b32_e32 v71, v215
	v_mov_b32_e32 v72, v216
	v_mov_b32_e32 v73, v217
	v_pk_fma_f32 v[18:19], v[64:65], v[64:65], v[18:19]
	v_pk_fma_f32 v[56:57], v[56:57], v[56:57], v[60:61]
	v_pk_fma_f32 v[18:19], v[62:63], v[62:63], v[18:19]
	v_pk_fma_f32 v[54:55], v[54:55], v[54:55], v[56:57]
	v_pk_fma_f32 v[18:19], v[58:59], v[58:59], v[18:19]
	v_pk_fma_f32 v[52:53], v[52:53], v[52:53], v[54:55]
	v_add_f32_e32 v18, v18, v19
	v_add_f32_e32 v18, v53, v18
	v_add_f32_e32 v18, v52, v18
	ds_bpermute_b32 v19, v27, v18
	v_ashrrev_i32_e32 v51, 31, v50
	v_lshl_add_u64 v[16:17], v[22:23], 0, v[16:17]
	s_waitcnt lgkmcnt(0)
	v_add_f32_e32 v18, v18, v19
	ds_swizzle_b32 v19, v18 offset:swizzle(SWAP,16)
	s_waitcnt lgkmcnt(0)
	v_add_f32_e32 v18, v18, v19
	ds_swizzle_b32 v19, v18 offset:swizzle(SWAP,8)
	s_waitcnt lgkmcnt(0)
	v_add_f32_e32 v18, v18, v19
	ds_swizzle_b32 v19, v18 offset:swizzle(SWAP,4)
	s_waitcnt lgkmcnt(0)
	v_add_f32_e32 v18, v18, v19
	ds_swizzle_b32 v19, v18 offset:swizzle(SWAP,2)
	s_waitcnt lgkmcnt(0)
	v_add_f32_e32 v18, v18, v19
	ds_swizzle_b32 v19, v18 offset:swizzle(SWAP,1)
	s_waitcnt lgkmcnt(0)
	v_add_f32_e32 v18, v18, v19
	v_fmamk_f32 v18, v18, 0x3a800000, v189
	v_mul_f32_e32 v19, 0x4b800000, v18
	v_cmp_gt_f32_e32 vcc, s28, v18
	v_add_f32_e32 v12, 1.0, v12
	s_nop 0
	v_cndmask_b32_e32 v18, v18, v19, vcc
	v_rsq_f32_e32 v31, v18
	v_lshlrev_b64 v[18:19], 11, v[50:51]
	v_add_f32_e32 v13, 1.0, v13
	v_lshl_add_u64 v[54:55], v[36:37], 0, v[18:19]
	v_mul_f32_e32 v33, 0x45800000, v31
	v_cndmask_b32_e32 v31, v31, v33, vcc
	v_mul_f32_e32 v33, v49, v31
	v_mul_f32_e32 v35, v5, v31
	v_mul_f32_e32 v41, v47, v31
	v_mul_f32_e32 v50, v7, v31
	v_mul_f32_e32 v8, v8, v33
	v_mul_f32_e32 v9, v9, v35
	v_mul_f32_e32 v10, v10, v41
	v_mul_f32_e32 v11, v11, v50
	v_add_f32_e32 v14, 1.0, v14
	v_add_f32_e32 v15, 1.0, v15
	v_fma_f32 v8, v12, v8, v70
	v_fma_f32 v9, v13, v9, v71
	v_fma_f32 v10, v10, v14, v72
	v_fmac_f32_e32 v73, v11, v15
	v_cvt_pk_bf16_f32 v8, v8, v9
	v_cvt_pk_bf16_f32 v9, v10, v73
	global_store_dwordx2 v[54:55], v[8:9], off
	v_lshl_add_u64 v[18:19], v[22:23], 0, v[68:69]
	v_mov_b32_e32 v8, v202
	v_mov_b32_e32 v9, v203
	v_mov_b32_e32 v10, v204
	v_mov_b32_e32 v11, v205
	v_mov_b32_e32 v12, v240
	v_mov_b32_e32 v13, v241
	v_mov_b32_e32 v14, v242
	v_mov_b32_e32 v15, v243
	v_mov_b32_e32 v50, v218
	v_mov_b32_e32 v51, v219
	v_mov_b32_e32 v52, v220
	v_mov_b32_e32 v53, v221
	v_lshl_add_u64 v[18:19], v[22:23], 0, v[20:21]
	v_mul_f32_e32 v20, v48, v31
	v_mul_f32_e32 v21, v4, v31
	v_mul_f32_e32 v33, v46, v31
	v_mul_f32_e32 v35, v6, v31
	v_mul_f32_e32 v22, v45, v31
	v_mul_f32_e32 v23, v1, v31
	v_mul_f32_e32 v8, v20, v8
	v_add_f32_e32 v12, 1.0, v12
	v_mul_f32_e32 v9, v21, v9
	v_add_f32_e32 v13, 1.0, v13
	v_mul_f32_e32 v10, v33, v10
	v_add_f32_e32 v14, 1.0, v14
	v_mul_f32_e32 v11, v35, v11
	v_add_f32_e32 v15, 1.0, v15
	v_fma_f32 v8, v8, v12, v50
	v_fma_f32 v9, v9, v13, v51
	v_fma_f32 v10, v10, v14, v52
	v_fmac_f32_e32 v53, v11, v15
	v_cvt_pk_bf16_f32 v8, v8, v9
	v_cvt_pk_bf16_f32 v9, v10, v53
	global_store_dwordx2 v[54:55], v[8:9], off offset:512
	v_mov_b32_e32 v8, v206
	v_mov_b32_e32 v9, v207
	v_mov_b32_e32 v10, v208
	v_mov_b32_e32 v11, v209
	s_nop 0
	v_mov_b32_e32 v12, v244
	v_mov_b32_e32 v13, v245
	v_mov_b32_e32 v14, v246
	v_mov_b32_e32 v15, v247
	s_nop 0
	v_mov_b32_e32 v18, v222
	v_mov_b32_e32 v19, v223
	v_mov_b32_e32 v20, v224
	v_mov_b32_e32 v21, v225
	v_mul_f32_e32 v33, v43, v31
	v_mul_f32_e32 v35, v3, v31
	v_mul_f32_e32 v8, v22, v8
	v_add_f32_e32 v12, 1.0, v12
	v_mul_f32_e32 v9, v23, v9
	v_add_f32_e32 v13, 1.0, v13
	v_mul_f32_e32 v10, v33, v10
	v_add_f32_e32 v14, 1.0, v14
	v_mul_f32_e32 v11, v35, v11
	v_add_f32_e32 v15, 1.0, v15
	v_fma_f32 v8, v8, v12, v18
	v_fma_f32 v9, v9, v13, v19
	v_fma_f32 v10, v10, v14, v20
	v_fmac_f32_e32 v21, v11, v15
	v_cvt_pk_bf16_f32 v8, v8, v9
	v_cvt_pk_bf16_f32 v9, v10, v21
	global_store_dwordx2 v[54:55], v[8:9], off offset:1024
	v_mov_b32_e32 v8, v210
	v_mov_b32_e32 v9, v211
	v_mov_b32_e32 v10, v212
	v_mov_b32_e32 v11, v213
	s_nop 0
	v_mov_b32_e32 v12, v248
	v_mov_b32_e32 v13, v249
	v_mov_b32_e32 v14, v250
	v_mov_b32_e32 v15, v251
	s_nop 0
	v_mov_b32_e32 v16, v226
	v_mov_b32_e32 v17, v227
	v_mov_b32_e32 v18, v228
	v_mov_b32_e32 v19, v229
	v_mul_f32_e32 v20, v44, v31
	v_mul_f32_e32 v21, v0, v31
	v_mul_f32_e32 v22, v42, v31
	v_mul_f32_e32 v23, v2, v31
	v_mul_f32_e32 v8, v20, v8
	v_add_f32_e32 v12, 1.0, v12
	v_mul_f32_e32 v9, v21, v9
	v_add_f32_e32 v13, 1.0, v13
	v_mul_f32_e32 v10, v22, v10
	v_add_f32_e32 v14, 1.0, v14
	v_mul_f32_e32 v11, v23, v11
	v_add_f32_e32 v15, 1.0, v15
	v_fma_f32 v8, v8, v12, v16
	v_fma_f32 v9, v9, v13, v17
	v_fma_f32 v10, v10, v14, v18
	v_fmac_f32_e32 v19, v11, v15
	v_cvt_pk_bf16_f32 v8, v8, v9
	v_cvt_pk_bf16_f32 v9, v10, v19
	global_store_dwordx2 v[54:55], v[8:9], off offset:1536
	s_branch .LBB0_148

.LBB0_1329:
	v_mov_b32_e32 v0, v188
	v_mov_b32_e32 v2, 0x21d28
	v_readlane_b32 s0, v238, 7
	v_add_u32_e32 v2, 0, v2
	ds_read_b64 v[2:3], v2
	v_ashrrev_i32_e32 v1, 6, v0
	v_add_u32_e32 v28, s0, v1
	s_mov_b32 s0, 0xa000
	v_cmp_gt_i32_e32 vcc, s0, v28
	s_waitcnt lgkmcnt(0)
	v_readfirstlane_b32 s4, v2
	v_mov_b32_e32 v2, 0x21c40
	v_readfirstlane_b32 s2, v3
	v_add_u32_e32 v2, 0, v2
	ds_read_b64 v[2:3], v2
	s_waitcnt lgkmcnt(0)
	v_readfirstlane_b32 s6, v2
	v_mov_b32_e32 v2, 0x21d28
	v_readfirstlane_b32 s5, v3
	v_add_u32_e32 v2, 0, v2
	ds_read_b64 v[2:3], v2
	s_waitcnt lgkmcnt(0)
	v_readfirstlane_b32 s7, v3
	v_readfirstlane_b32 s8, v2
	s_and_saveexec_b64 s[0:1], vcc
	v_readlane_b32 s52, v236, 11
	v_readlane_b32 s44, v236, 3
	s_movk_i32 s50, 0x6000
	s_movk_i32 s48, 0x1fff
	v_readlane_b32 s53, v236, 12
	s_mov_b64 s[58:59], 0x1000
	v_readlane_b32 s45, v236, 4
	s_cbranch_execz .LBB0_1336
	s_add_u32 s8, s8, 0x6078000
	s_addc_u32 s9, s7, 0
	s_lshl_b32 s7, s52, 13
	s_add_u32 s6, s6, s7
	s_addc_u32 s5, s5, 0
	v_lshlrev_b32_e32 v1, 2, v0
	s_add_u32 s6, s6, 0x1000
	v_and_b32_e32 v30, 0xfc, v1
	s_addc_u32 s7, s5, 0
	v_lshlrev_b32_e32 v164, 2, v30
	v_or_b32_e32 v34, 0x100, v30
	v_lshl_add_u64 v[32:33], s[6:7], 0, v[164:165]
	v_lshlrev_b32_e32 v164, 2, v34
	v_or_b32_e32 v38, 0x200, v30
	v_lshl_add_u64 v[36:37], s[6:7], 0, v[164:165]
	v_lshlrev_b32_e32 v164, 2, v38
	v_or_b32_e32 v42, 0x300, v30
	v_ashrrev_i32_e32 v29, 31, v28
	v_lshl_add_u64 v[40:41], s[6:7], 0, v[164:165]
	v_lshlrev_b32_e32 v164, 2, v42
	v_lshlrev_b64 v[2:3], 11, v[28:29]
	v_and_b32_e32 v0, 63, v0
	s_movk_i32 s5, 0x80
	s_add_u32 s4, s4, 0x2bc3000
	v_lshl_add_u64 v[44:45], s[6:7], 0, v[164:165]
	v_lshlrev_b32_e32 v164, 1, v30
	v_lshl_or_b32 v2, v0, 3, v2
	v_lshlrev_b64 v[50:51], 12, v[28:29]
	v_bitop3_b32 v31, v1, s5, v193 bitop3:0x6c
	s_addc_u32 s5, s2, 0
	v_lshl_add_u64 v[46:47], s[8:9], 0, v[164:165]
	v_lshl_add_u64 v[48:49], s[8:9], 0, v[2:3]
	v_lshl_or_b32 v50, v0, 4, v50
	s_mov_b64 s[8:9], 0
	global_load_dwordx4 v[198:201], v[32:33], off
	global_load_dwordx4 v[202:205], v[36:37], off
	global_load_dwordx4 v[206:209], v[40:41], off
	global_load_dwordx4 v[210:213], v[44:45], off
	s_mul_i32 s100, s86, 0x6000
	s_add_u32 s100, s4, s100
	s_addc_u32 s101, s5, 0
	v_lshlrev_b32_e32 v234, 4, v188
	global_load_dwordx4 v[214:217], v234, s[100:101]
	s_add_u32 s100, s100, 0x6000
	s_addc_u32 s101, s101, 0
	global_load_dwordx4 v[218:221], v234, s[100:101]
	s_add_u32 s100, s100, 0x6000
	s_addc_u32 s101, s101, 0
	global_load_dwordx4 v[222:225], v234, s[100:101]
	s_add_u32 s100, s100, 0x6000
	s_addc_u32 s101, s101, 0
	global_load_dwordx4 v[226:229], v234, s[100:101]
	s_add_u32 s100, s100, 0x6000
	s_addc_u32 s101, s101, 0
	global_load_dwordx4 v[230:233], v234, s[100:101]
	s_add_u32 s100, s100, 0x6000
	s_addc_u32 s101, s101, 0
	global_load_dwordx4 v[240:243], v234, s[100:101]
	s_add_u32 s100, s100, 0x6000
	s_addc_u32 s101, s101, 0
	global_load_dwordx4 v[244:247], v234, s[100:101]
	s_add_u32 s100, s100, 0x6000
	s_addc_u32 s101, s101, 0
	global_load_dwordx4 v[248:251], v234, s[100:101]
	s_add_u32 s100, s100, 0x6000
	s_addc_u32 s101, s101, 0
	global_load_dwordx4 v[252:255], v234, s[100:101]
	s_add_u32 s100, s100, 0x6000
	s_addc_u32 s101, s101, 0
	s_sub_u32 s101, s100, 0x35000
	v_add_u32_e32 v235, 0xa000, v234
	v_add_u32_e32 v234, 0xc000, v234
	s_waitcnt vmcnt(0)
	ds_write_b128 v235, v[214:217]
	ds_write_b128 v235, v[218:221] offset:8192
	ds_write_b128 v235, v[222:225] offset:16384
	ds_write_b128 v235, v[226:229] offset:24576
	ds_write_b128 v235, v[230:233] offset:32768
	ds_write_b128 v235, v[240:243] offset:40960
	ds_write_b128 v235, v[244:247] offset:49152
	ds_write_b128 v235, v[248:251] offset:57344
	ds_write_b128 v234, v[252:255] offset:57344
	s_waitcnt lgkmcnt(0)
	s_barrier
	s_branch .LBB0_1332

.LBB0_1334:
	s_or_b64 exec, exec, s[10:11]
	s_waitcnt vmcnt(3)
	v_mov_b32_e32 v26, v21
	s_waitcnt vmcnt(2)
	v_mov_b32_e32 v27, v17
	v_mov_b32_e32 v24, v20
	v_mov_b32_e32 v25, v16
	v_pk_mul_f32 v[26:27], v[26:27], v[26:27]
	v_mov_b32_e32 v78, v22
	v_mov_b32_e32 v79, v18
	v_pk_fma_f32 v[24:25], v[24:25], v[24:25], v[26:27]
	v_mov_b32_e32 v80, v23
	v_pk_fma_f32 v[24:25], v[78:79], v[78:79], v[24:25]
	s_waitcnt vmcnt(1)
	v_mov_b32_e32 v78, v13
	s_waitcnt vmcnt(0)
	v_mov_b32_e32 v79, v9
	v_mov_b32_e32 v81, v19
	v_mov_b32_e32 v26, v12
	v_mov_b32_e32 v27, v8
	v_pk_mul_f32 v[78:79], v[78:79], v[78:79]
	v_pk_fma_f32 v[24:25], v[80:81], v[80:81], v[24:25]
	v_mov_b32_e32 v80, v14
	v_mov_b32_e32 v81, v10
	v_pk_fma_f32 v[26:27], v[26:27], v[26:27], v[78:79]
	v_mov_b32_e32 v82, v15
	v_mov_b32_e32 v83, v11
	v_pk_fma_f32 v[26:27], v[80:81], v[80:81], v[26:27]
	v_add_f32_e32 v24, v24, v25
	v_pk_fma_f32 v[26:27], v[82:83], v[82:83], v[26:27]
	s_nop 0
	v_add_f32_e32 v24, v24, v26
	v_add_f32_e32 v24, v24, v27
	ds_bpermute_b32 v25, v31, v24
	s_waitcnt lgkmcnt(0)
	v_add_f32_e32 v24, v24, v25
	ds_swizzle_b32 v25, v24 offset:swizzle(SWAP,16)
	s_waitcnt lgkmcnt(0)
	v_add_f32_e32 v24, v24, v25
	ds_swizzle_b32 v25, v24 offset:swizzle(SWAP,8)
	s_waitcnt lgkmcnt(0)
	v_add_f32_e32 v24, v24, v25
	ds_swizzle_b32 v25, v24 offset:swizzle(SWAP,4)
	s_waitcnt lgkmcnt(0)
	v_add_f32_e32 v24, v24, v25
	ds_swizzle_b32 v25, v24 offset:swizzle(SWAP,2)
	s_waitcnt lgkmcnt(0)
	v_add_f32_e32 v24, v24, v25
	ds_swizzle_b32 v25, v24 offset:swizzle(SWAP,1)
	s_waitcnt lgkmcnt(0)
	v_add_f32_e32 v24, v24, v25
	v_fmamk_f32 v24, v24, 0x3a800000, v189
	v_cmp_gt_f32_e64 s[34:35], s28, v24
	v_mul_f32_e32 v25, 0x4b800000, v24
	s_nop 0
	v_cndmask_b32_e64 v24, v24, v25, s[34:35]
	v_rsq_f32_e32 v24, v24
	s_nop 0
	v_mul_f32_e32 v25, 0x45800000, v24
	v_cndmask_b32_e64 v29, v24, v25, s[34:35]
	v_add_u32_e32 v24, 0xffffe000, v28
	v_lshrrev_b32_e32 v24, 12, v24
	v_add_u32_e32 v24, 1, v24
	v_cmp_lt_i32_e64 s[34:35], s48, v28
	v_mul_f32_e32 v20, v20, v29
	v_mul_f32_e32 v21, v21, v29
	v_cndmask_b32_e64 v24, 0, v24, s[34:35]
	v_add_u32_e32 v26, s86, v24
	v_mov_b64_e32 v[24:25], s[4:5]
	v_mad_u64_u32 v[78:79], s[6:7], v26, s50, v[24:25]
	v_lshl_add_u64 v[80:81], v[78:79], 0, s[58:59]
	v_lshl_add_u64 v[82:83], v[78:79], 0, v[164:165]
	v_lshl_add_u64 v[78:79], v[80:81], 0, v[164:165]
	v_mov_b32_e32 v252, v78
	v_mov_b32_e32 v253, v79
	v_subrev_u32_e32 v234, s101, v252
	v_lshrrev_b32_e32 v235, 13, v234
	v_mul_u32_u24_e32 v235, 0xab, v235
	v_lshrrev_b32_e32 v235, 9, v235
	v_and_b32_e32 v234, 0x1fff, v234
	v_lshl_add_u32 v234, v235, 13, v234
	v_add_u32_e32 v234, 0xa000, v234
	ds_read_b128 v[214:217], v234
	ds_read_b128 v[218:221], v234 offset:1024
	ds_read_b128 v[222:225], v234 offset:2048
	ds_read_b128 v[226:229], v234 offset:3072
	ds_read_b128 v[230:233], v234 offset:4096
	ds_read_b128 v[240:243], v234 offset:5120
	ds_read_b128 v[244:247], v234 offset:6144
	ds_read_b128 v[248:251], v234 offset:7168
	s_waitcnt vmcnt(0) lgkmcnt(0)
	v_mov_b32_e32 v24, v198
	v_mov_b32_e32 v25, v199
	v_mov_b32_e32 v26, v200
	v_mov_b32_e32 v27, v201
	v_mov_b32_e32 v84, v214
	v_mov_b32_e32 v85, v215
	v_mov_b32_e32 v86, v216
	v_mov_b32_e32 v87, v217
	v_mov_b32_e32 v88, v230
	v_mov_b32_e32 v89, v231
	v_mov_b32_e32 v90, v232
	v_mov_b32_e32 v91, v233
	v_mul_f32_e32 v22, v22, v29
	v_mul_f32_e32 v23, v23, v29
	v_lshlrev_b32_e32 v78, 2, v34
	v_mov_b32_e32 v79, v165
	v_mul_f32_e32 v16, v16, v29
	v_mul_f32_e32 v17, v17, v29
	v_mul_f32_e32 v18, v18, v29
	v_mul_f32_e32 v19, v19, v29
	v_mul_f32_e32 v12, v12, v29
	v_mul_f32_e32 v13, v13, v29
	v_mul_f32_e32 v14, v14, v29
	v_mul_f32_e32 v15, v15, v29
	v_mul_f32_e32 v8, v8, v29
	v_mul_f32_e32 v9, v9, v29
	v_mul_f32_e32 v10, v10, v29
	v_mul_f32_e32 v11, v11, v29
	v_mul_f32_e32 v20, v24, v20
	v_mul_f32_e32 v21, v25, v21
	v_add_f32_e32 v24, 1.0, v88
	v_fma_f32 v20, v24, v20, v84
	v_add_f32_e32 v24, 1.0, v89
	v_fma_f32 v21, v24, v21, v85
	v_mul_f32_e32 v22, v26, v22
	v_add_f32_e32 v24, 1.0, v90
	v_fma_f32 v22, v22, v24, v86
	v_mul_f32_e32 v23, v27, v23
	v_add_f32_e32 v24, 1.0, v91
	v_fmac_f32_e32 v87, v23, v24
	v_cvt_pk_bf16_f32 v20, v20, v21
	v_cvt_pk_bf16_f32 v21, v22, v87
	global_store_dwordx2 v[48:49], v[20:21], off
	v_lshl_add_u64 v[84:85], v[80:81], 0, v[78:79]
	v_mov_b32_e32 v24, v202
	v_mov_b32_e32 v25, v203
	v_mov_b32_e32 v26, v204
	v_mov_b32_e32 v27, v205
	v_mov_b32_e32 v20, v218
	v_mov_b32_e32 v21, v219
	v_mov_b32_e32 v22, v220
	v_mov_b32_e32 v23, v221
	v_mul_f32_e32 v16, v16, v24
	v_mov_b32_e32 v84, v240
	v_mov_b32_e32 v85, v241
	v_mov_b32_e32 v86, v242
	v_mov_b32_e32 v87, v243
	v_mul_f32_e32 v17, v17, v25
	v_mul_f32_e32 v18, v18, v26
	v_mul_f32_e32 v19, v19, v27
	v_add_f32_e32 v24, 1.0, v84
	v_fma_f32 v16, v16, v24, v20
	v_add_f32_e32 v20, 1.0, v85
	v_fma_f32 v17, v17, v20, v21
	v_add_f32_e32 v20, 1.0, v86
	v_fma_f32 v18, v18, v20, v22
	v_add_f32_e32 v20, 1.0, v87
	v_fmac_f32_e32 v23, v19, v20
	v_lshlrev_b32_e32 v20, 2, v38
	v_mov_b32_e32 v21, v165
	v_cvt_pk_bf16_f32 v16, v16, v17
	v_cvt_pk_bf16_f32 v17, v18, v23
	global_store_dwordx2 v[48:49], v[16:17], off offset:512
	v_lshl_add_u64 v[26:27], v[80:81], 0, v[20:21]
	v_mov_b32_e32 v16, v206
	v_mov_b32_e32 v17, v207
	v_mov_b32_e32 v18, v208
	v_mov_b32_e32 v19, v209
	v_mov_b32_e32 v22, v222
	v_mov_b32_e32 v23, v223
	v_mov_b32_e32 v24, v224
	v_mov_b32_e32 v25, v225
	v_mov_b32_e32 v84, v244
	v_mov_b32_e32 v85, v245
	v_mov_b32_e32 v86, v246
	v_mov_b32_e32 v87, v247
	v_mul_f32_e32 v12, v12, v16
	v_mul_f32_e32 v13, v13, v17
	v_add_f32_e32 v16, 1.0, v84
	v_fma_f32 v12, v12, v16, v22
	v_add_f32_e32 v16, 1.0, v85
	v_fma_f32 v13, v13, v16, v23
	v_mul_f32_e32 v14, v14, v18
	v_add_f32_e32 v16, 1.0, v86
	v_fma_f32 v14, v14, v16, v24
	v_mul_f32_e32 v15, v15, v19
	v_add_f32_e32 v16, 1.0, v87
	v_fmac_f32_e32 v25, v15, v16
	v_lshlrev_b32_e32 v22, 2, v42
	v_mov_b32_e32 v23, v165
	v_cvt_pk_bf16_f32 v12, v12, v13
	v_cvt_pk_bf16_f32 v13, v14, v25
	global_store_dwordx2 v[48:49], v[12:13], off offset:1024
	v_lshl_add_u64 v[24:25], v[80:81], 0, v[22:23]
	v_mov_b32_e32 v16, v210
	v_mov_b32_e32 v17, v211
	v_mov_b32_e32 v18, v212
	v_mov_b32_e32 v19, v213
	v_mov_b32_e32 v12, v226
	v_mov_b32_e32 v13, v227
	v_mov_b32_e32 v14, v228
	v_mov_b32_e32 v15, v229
	v_mul_f32_e32 v8, v8, v16
	v_mov_b32_e32 v24, v248
	v_mov_b32_e32 v25, v249
	v_mov_b32_e32 v26, v250
	v_mov_b32_e32 v27, v251
	v_mul_f32_e32 v9, v9, v17
	v_mul_f32_e32 v10, v10, v18
	v_mul_f32_e32 v11, v11, v19
	v_add_f32_e32 v16, 1.0, v24
	v_fma_f32 v8, v8, v16, v12
	v_add_f32_e32 v12, 1.0, v25
	v_fma_f32 v9, v9, v12, v13
	v_add_f32_e32 v12, 1.0, v26
	v_fma_f32 v10, v10, v12, v14
	v_add_f32_e32 v12, 1.0, v27
	v_fmac_f32_e32 v15, v11, v12
	v_cvt_pk_bf16_f32 v8, v8, v9
	v_cvt_pk_bf16_f32 v9, v10, v15
	global_store_dwordx2 v[48:49], v[8:9], off offset:1536
	s_and_saveexec_b64 s[10:11], vcc
	s_cbranch_execz .LBB0_1331
	v_pk_mul_f32 v[8:9], v[76:77], v[76:77]
	v_pk_mul_f32 v[10:11], v[68:69], v[68:69]
	v_pk_fma_f32 v[8:9], v[74:75], v[74:75], v[8:9]
	v_pk_fma_f32 v[10:11], v[66:67], v[66:67], v[10:11]
	v_pk_fma_f32 v[8:9], v[72:73], v[72:73], v[8:9]
	v_pk_fma_f32 v[10:11], v[64:65], v[64:65], v[10:11]
	v_pk_fma_f32 v[8:9], v[70:71], v[70:71], v[8:9]
	v_pk_fma_f32 v[10:11], v[62:63], v[62:63], v[10:11]
	v_add_f32_e32 v8, v8, v9
	v_add_f32_e32 v8, v11, v8
	v_add_f32_e32 v8, v10, v8
	ds_bpermute_b32 v9, v31, v8
	v_lshlrev_b64 v[14:15], 11, v[60:61]
	s_waitcnt lgkmcnt(0)
	v_add_f32_e32 v8, v8, v9
	ds_swizzle_b32 v9, v8 offset:swizzle(SWAP,16)
	s_waitcnt lgkmcnt(0)
	v_add_f32_e32 v8, v8, v9
	ds_swizzle_b32 v9, v8 offset:swizzle(SWAP,8)
	s_waitcnt lgkmcnt(0)
	v_add_f32_e32 v8, v8, v9
	ds_swizzle_b32 v9, v8 offset:swizzle(SWAP,4)
	s_waitcnt lgkmcnt(0)
	v_add_f32_e32 v8, v8, v9
	ds_swizzle_b32 v9, v8 offset:swizzle(SWAP,2)
	s_waitcnt lgkmcnt(0)
	v_add_f32_e32 v8, v8, v9
	ds_swizzle_b32 v9, v8 offset:swizzle(SWAP,1)
	s_waitcnt lgkmcnt(0)
	v_add_f32_e32 v8, v8, v9
	v_fmamk_f32 v8, v8, 0x3a800000, v189
	v_cmp_gt_f32_e32 vcc, s28, v8
	v_mul_f32_e32 v9, 0x4b800000, v8
	s_nop 0
	v_cndmask_b32_e32 v8, v8, v9, vcc
	v_rsq_f32_e32 v8, v8
	s_nop 0
	v_mul_f32_e32 v9, 0x45800000, v8
	v_cndmask_b32_e32 v24, v8, v9, vcc
	v_add_u32_e32 v8, 0xffffe000, v60
	v_lshrrev_b32_e32 v8, 12, v8
	v_add_u32_e32 v8, 1, v8
	v_cmp_lt_i32_e32 vcc, s48, v60
	s_nop 1
	v_cndmask_b32_e32 v8, 0, v8, vcc
	v_add_u32_e32 v10, s86, v8
	v_mov_b64_e32 v[8:9], s[4:5]
	v_mad_u64_u32 v[8:9], s[6:7], v10, s50, v[8:9]
	v_lshl_add_u64 v[16:17], v[8:9], 0, s[58:59]
	v_lshl_add_u64 v[8:9], v[8:9], 0, v[164:165]
	v_lshl_add_u64 v[18:19], v[16:17], 0, v[164:165]
	v_mov_b32_e32 v254, v18
	v_mov_b32_e32 v255, v19
	v_cmp_ne_u64_e32 vcc, v[254:255], v[252:253]
	s_nop 1
	s_and_b64 vcc, exec, vcc
	s_cbranch_vccz .Lnorm_same_cond_2
	v_subrev_u32_e32 v234, s101, v254
	v_lshrrev_b32_e32 v235, 13, v234
	v_mul_u32_u24_e32 v235, 0xab, v235
	v_lshrrev_b32_e32 v235, 9, v235
	v_and_b32_e32 v234, 0x1fff, v234
	v_lshl_add_u32 v234, v235, 13, v234
	v_add_u32_e32 v234, 0xa000, v234
	ds_read_b128 v[214:217], v234
	ds_read_b128 v[218:221], v234 offset:1024
	ds_read_b128 v[222:225], v234 offset:2048
	ds_read_b128 v[226:229], v234 offset:3072
	ds_read_b128 v[230:233], v234 offset:4096
	ds_read_b128 v[240:243], v234 offset:5120
	ds_read_b128 v[244:247], v234 offset:6144
	ds_read_b128 v[248:251], v234 offset:7168
.Lnorm_same_cond_2:
	s_waitcnt vmcnt(0) lgkmcnt(0)
	v_mov_b32_e32 v10, v198
	v_mov_b32_e32 v11, v199
	v_mov_b32_e32 v12, v200
	v_mov_b32_e32 v13, v201
	v_mov_b32_e32 v60, v214
	v_mov_b32_e32 v61, v215
	v_mov_b32_e32 v62, v216
	v_mov_b32_e32 v63, v217
	v_mov_b32_e32 v64, v230
	v_mov_b32_e32 v65, v231
	v_mov_b32_e32 v66, v232
	v_mov_b32_e32 v67, v233
	v_mul_f32_e32 v18, v5, v24
	v_mul_f32_e32 v10, v10, v18
	v_add_f32_e32 v18, 1.0, v64
	v_fma_f32 v10, v18, v10, v60
	v_mul_f32_e32 v18, v59, v24
	v_mul_f32_e32 v11, v11, v18
	v_add_f32_e32 v18, 1.0, v65
	v_fma_f32 v11, v18, v11, v61
	v_mul_f32_e32 v18, v7, v24
	v_mul_f32_e32 v12, v12, v18
	v_add_f32_e32 v18, 1.0, v66
	v_fma_f32 v12, v12, v18, v62
	v_mul_f32_e32 v18, v57, v24
	v_mul_f32_e32 v13, v13, v18
	v_add_f32_e32 v18, 1.0, v67
	v_fmac_f32_e32 v63, v13, v18
	v_lshl_add_u64 v[18:19], v[46:47], 0, v[14:15]
	v_cvt_pk_bf16_f32 v10, v10, v11
	v_cvt_pk_bf16_f32 v11, v12, v63
	global_store_dwordx2 v[18:19], v[10:11], off
	v_lshl_add_u64 v[14:15], v[16:17], 0, v[78:79]
	v_mov_b32_e32 v10, v202
	v_mov_b32_e32 v11, v203
	v_mov_b32_e32 v12, v204
	v_mov_b32_e32 v13, v205
	v_mov_b32_e32 v60, v218
	v_mov_b32_e32 v61, v219
	v_mov_b32_e32 v62, v220
	v_mov_b32_e32 v63, v221
	v_mov_b32_e32 v64, v240
	v_mov_b32_e32 v65, v241
	v_mov_b32_e32 v66, v242
	v_mov_b32_e32 v67, v243
	v_mul_f32_e32 v14, v4, v24
	v_mul_f32_e32 v10, v14, v10
	v_add_f32_e32 v14, 1.0, v64
	v_fma_f32 v10, v10, v14, v60
	v_mul_f32_e32 v14, v58, v24
	v_mul_f32_e32 v11, v14, v11
	v_add_f32_e32 v14, 1.0, v65
	v_fma_f32 v11, v11, v14, v61
	v_mul_f32_e32 v14, v6, v24
	v_mul_f32_e32 v12, v14, v12
	v_add_f32_e32 v14, 1.0, v66
	v_fma_f32 v12, v12, v14, v62
	v_mul_f32_e32 v14, v56, v24
	v_mul_f32_e32 v13, v14, v13
	v_add_f32_e32 v14, 1.0, v67
	v_fmac_f32_e32 v63, v13, v14
	v_cvt_pk_bf16_f32 v10, v10, v11
	v_cvt_pk_bf16_f32 v11, v12, v63
	global_store_dwordx2 v[18:19], v[10:11], off offset:512
	v_lshl_add_u64 v[14:15], v[16:17], 0, v[20:21]
	v_mov_b32_e32 v10, v206
	v_mov_b32_e32 v11, v207
	v_mov_b32_e32 v12, v208
	v_mov_b32_e32 v13, v209
	v_mov_b32_e32 v60, v222
	v_mov_b32_e32 v61, v223
	v_mov_b32_e32 v62, v224
	v_mov_b32_e32 v63, v225
	v_mov_b32_e32 v64, v244
	v_mov_b32_e32 v65, v245
	v_mov_b32_e32 v66, v246
	v_mov_b32_e32 v67, v247
	v_mul_f32_e32 v14, v1, v24
	v_lshl_add_u64 v[16:17], v[16:17], 0, v[22:23]
	v_mul_f32_e32 v10, v14, v10
	v_add_f32_e32 v14, 1.0, v64
	v_fma_f32 v10, v10, v14, v60
	v_mul_f32_e32 v14, v55, v24
	v_mul_f32_e32 v11, v14, v11
	v_add_f32_e32 v14, 1.0, v65
	v_fma_f32 v11, v11, v14, v61
	v_mul_f32_e32 v14, v3, v24
	v_mul_f32_e32 v12, v14, v12
	v_add_f32_e32 v14, 1.0, v66
	v_fma_f32 v12, v12, v14, v62
	v_mul_f32_e32 v14, v53, v24
	v_mul_f32_e32 v13, v14, v13
	v_add_f32_e32 v14, 1.0, v67
	v_fmac_f32_e32 v63, v13, v14
	v_cvt_pk_bf16_f32 v10, v10, v11
	v_cvt_pk_bf16_f32 v11, v12, v63
	global_store_dwordx2 v[18:19], v[10:11], off offset:1024
	v_mov_b32_e32 v12, v210
	v_mov_b32_e32 v13, v211
	v_mov_b32_e32 v14, v212
	v_mov_b32_e32 v15, v213
	s_nop 0
	v_mov_b32_e32 v8, v226
	v_mov_b32_e32 v9, v227
	v_mov_b32_e32 v10, v228
	v_mov_b32_e32 v11, v229
	s_nop 0
	v_mov_b32_e32 v20, v248
	v_mov_b32_e32 v21, v249
	v_mov_b32_e32 v22, v250
	v_mov_b32_e32 v23, v251
	v_mul_f32_e32 v16, v0, v24
	v_mul_f32_e32 v12, v16, v12
	v_add_f32_e32 v16, 1.0, v20
	v_fma_f32 v8, v12, v16, v8
	v_mul_f32_e32 v12, v54, v24
	v_mul_f32_e32 v12, v12, v13
	v_add_f32_e32 v13, 1.0, v21
	v_fma_f32 v9, v12, v13, v9
	v_mul_f32_e32 v12, v2, v24
	v_mul_f32_e32 v12, v12, v14
	v_add_f32_e32 v13, 1.0, v22
	v_fma_f32 v10, v12, v13, v10
	v_mul_f32_e32 v12, v52, v24
	v_mul_f32_e32 v12, v12, v15
	v_add_f32_e32 v13, 1.0, v23
	v_fmac_f32_e32 v11, v12, v13
	v_cvt_pk_bf16_f32 v8, v8, v9
	v_cvt_pk_bf16_f32 v9, v10, v11
	global_store_dwordx2 v[18:19], v[8:9], off offset:1536
	s_branch .LBB0_1331
